# pk_mov zeroing in the remaining 4 GEMM unit loops (all 17 now)
# speedup vs baseline: 1.0152x; 1.0078x over previous
; #define PG8_BAR __builtin_amdgcn_s_barrier()
; template <class Epi>
; __device__ __forceinline__ void gemm_phase(LAS unsigned char* lds, const int tid, const Gemm g, const StaticOrder& S, const Epi& E) {
;     ...
;                 const char* sp = (const char*)E.ss + (size_t)cur.pm * (256 * 64) + (size_t)tid * 16;
;     ...
; #pragma unroll
;         for (int a = 0; a < 2; ++a)
; #pragma unroll
;             for (int b = 0; b < 2; ++b)
; #pragma unroll
;                 for (int m = 0; m < 4; ++m)
; #pragma unroll
;                     for (int n = 0; n < 2; ++n) acc[a][b][m][n] = (f32x4){0.f, 0.f, 0.f, 0.f};
;         cur = nxt; cA = nA; cB = nB; ++ui;
;         if (wr == 1) PG8_BAR;
.Lzskip_2:
	s_and_b64 s[40:41], s[2:3], exec
	s_cselect_b32 s4, s29, s39
	s_cselect_b32 s25, s28, s38
	s_cselect_b32 s27, s31, s37
	s_cselect_b32 s66, s30, s36
	s_ashr_i32 s35, s34, 31
	s_lshl_b64 s[40:41], s[34:35], 14
	s_add_u32 s35, s36, 0x100
	s_addc_u32 s67, s37, 0
	v_lshl_add_u64 v[150:151], v[140:141], 0, s[40:41]
	s_add_u32 s36, s38, 0x40080
	v_mov_b32_e32 v0, 0
	v_mov_b32_e32 v1, 0
	v_lshl_add_u64 v[152:153], v[150:151], 0, s[22:23]
	s_addc_u32 s37, s39, 0
	s_mov_b32 s68, 0
	v_pk_mov_b32 v[2:3], v[0:1], v[0:1]
	v_pk_mov_b32 v[4:5], v[0:1], v[0:1]
	v_pk_mov_b32 v[6:7], v[0:1], v[0:1]
	v_pk_mov_b32 v[8:9], v[0:1], v[0:1]
	v_pk_mov_b32 v[10:11], v[0:1], v[0:1]
	v_pk_mov_b32 v[12:13], v[0:1], v[0:1]
	v_pk_mov_b32 v[14:15], v[0:1], v[0:1]
	v_pk_mov_b32 v[16:17], v[0:1], v[0:1]
	v_pk_mov_b32 v[18:19], v[0:1], v[0:1]
	v_pk_mov_b32 v[20:21], v[0:1], v[0:1]
	v_pk_mov_b32 v[22:23], v[0:1], v[0:1]
	v_pk_mov_b32 v[24:25], v[0:1], v[0:1]
	v_pk_mov_b32 v[26:27], v[0:1], v[0:1]
	v_pk_mov_b32 v[28:29], v[0:1], v[0:1]
	v_pk_mov_b32 v[30:31], v[0:1], v[0:1]
	v_pk_mov_b32 v[32:33], v[0:1], v[0:1]
	v_pk_mov_b32 v[34:35], v[0:1], v[0:1]
	v_pk_mov_b32 v[36:37], v[0:1], v[0:1]
	v_pk_mov_b32 v[38:39], v[0:1], v[0:1]
	v_pk_mov_b32 v[40:41], v[0:1], v[0:1]
	v_pk_mov_b32 v[42:43], v[0:1], v[0:1]
	v_pk_mov_b32 v[44:45], v[0:1], v[0:1]
	v_pk_mov_b32 v[46:47], v[0:1], v[0:1]
	v_pk_mov_b32 v[48:49], v[0:1], v[0:1]
	v_pk_mov_b32 v[50:51], v[0:1], v[0:1]
	v_pk_mov_b32 v[52:53], v[0:1], v[0:1]
	v_pk_mov_b32 v[54:55], v[0:1], v[0:1]
	v_pk_mov_b32 v[56:57], v[0:1], v[0:1]
	v_pk_mov_b32 v[58:59], v[0:1], v[0:1]
	v_pk_mov_b32 v[60:61], v[0:1], v[0:1]
	v_pk_mov_b32 v[62:63], v[0:1], v[0:1]
	v_pk_mov_b32 v[64:65], v[0:1], v[0:1]
	v_pk_mov_b32 v[66:67], v[0:1], v[0:1]
	v_pk_mov_b32 v[68:69], v[0:1], v[0:1]
	v_pk_mov_b32 v[70:71], v[0:1], v[0:1]
	v_pk_mov_b32 v[72:73], v[0:1], v[0:1]
	v_pk_mov_b32 v[74:75], v[0:1], v[0:1]
	v_pk_mov_b32 v[76:77], v[0:1], v[0:1]
	v_pk_mov_b32 v[78:79], v[0:1], v[0:1]
	v_pk_mov_b32 v[80:81], v[0:1], v[0:1]
	v_pk_mov_b32 v[82:83], v[0:1], v[0:1]
	v_pk_mov_b32 v[84:85], v[0:1], v[0:1]
	v_pk_mov_b32 v[86:87], v[0:1], v[0:1]
	v_pk_mov_b32 v[88:89], v[0:1], v[0:1]
	v_pk_mov_b32 v[90:91], v[0:1], v[0:1]
	v_pk_mov_b32 v[92:93], v[0:1], v[0:1]
	v_pk_mov_b32 v[94:95], v[0:1], v[0:1]
	v_pk_mov_b32 v[96:97], v[0:1], v[0:1]
	v_pk_mov_b32 v[98:99], v[0:1], v[0:1]
	v_pk_mov_b32 v[100:101], v[0:1], v[0:1]
	v_pk_mov_b32 v[102:103], v[0:1], v[0:1]
	v_pk_mov_b32 v[104:105], v[0:1], v[0:1]
	v_pk_mov_b32 v[106:107], v[0:1], v[0:1]
	v_pk_mov_b32 v[108:109], v[0:1], v[0:1]
	v_pk_mov_b32 v[110:111], v[0:1], v[0:1]
	v_pk_mov_b32 v[112:113], v[0:1], v[0:1]
	v_pk_mov_b32 v[114:115], v[0:1], v[0:1]
	v_pk_mov_b32 v[116:117], v[0:1], v[0:1]
	v_pk_mov_b32 v[118:119], v[0:1], v[0:1]
	v_pk_mov_b32 v[120:121], v[0:1], v[0:1]
	v_pk_mov_b32 v[122:123], v[0:1], v[0:1]
	v_pk_mov_b32 v[124:125], v[0:1], v[0:1]
	v_pk_mov_b32 v[126:127], v[0:1], v[0:1]
	s_branch .LBB0_443

; #define PG8_BAR __builtin_amdgcn_s_barrier()
; template <class Epi>
; __device__ __forceinline__ void gemm_phase(LAS unsigned char* lds, const int tid, const Gemm g, const StaticOrder& S, const Epi& E) {
;     ...
;                 const char* sp = (const char*)E.ss + (size_t)cur.pm * (256 * 64) + (size_t)tid * 16;
;     ...
; #pragma unroll
;         for (int a = 0; a < 2; ++a)
; #pragma unroll
;             for (int b = 0; b < 2; ++b)
; #pragma unroll
;                 for (int m = 0; m < 4; ++m)
; #pragma unroll
;                     for (int n = 0; n < 2; ++n) acc[a][b][m][n] = (f32x4){0.f, 0.f, 0.f, 0.f};
;         cur = nxt; cA = nA; cB = nB; ++ui;
;         if (wr == 1) PG8_BAR;
.Lzskip_6:
	s_and_b64 s[42:43], s[4:5], exec
	s_cselect_b32 s27, s31, s41
	s_cselect_b32 s29, s30, s40
	s_cselect_b32 s33, s35, s39
	s_cselect_b32 s62, s34, s38
	s_ashr_i32 s37, s36, 31
	s_lshl_b64 s[42:43], s[36:37], 14
	s_add_u32 s37, s38, 0x100
	s_addc_u32 s63, s39, 0
	v_lshl_add_u64 v[128:129], v[188:189], 0, s[42:43]
	s_add_u32 s38, s40, 0x40080
	v_mov_b32_e32 v0, 0
	v_mov_b32_e32 v1, 0
	v_lshl_add_u64 v[130:131], v[128:129], 0, s[6:7]
	s_addc_u32 s39, s41, 0
	s_mov_b32 s64, 0
	v_pk_mov_b32 v[2:3], v[0:1], v[0:1]
	v_pk_mov_b32 v[4:5], v[0:1], v[0:1]
	v_pk_mov_b32 v[6:7], v[0:1], v[0:1]
	v_pk_mov_b32 v[8:9], v[0:1], v[0:1]
	v_pk_mov_b32 v[10:11], v[0:1], v[0:1]
	v_pk_mov_b32 v[12:13], v[0:1], v[0:1]
	v_pk_mov_b32 v[14:15], v[0:1], v[0:1]
	v_pk_mov_b32 v[16:17], v[0:1], v[0:1]
	v_pk_mov_b32 v[18:19], v[0:1], v[0:1]
	v_pk_mov_b32 v[20:21], v[0:1], v[0:1]
	v_pk_mov_b32 v[22:23], v[0:1], v[0:1]
	v_pk_mov_b32 v[24:25], v[0:1], v[0:1]
	v_pk_mov_b32 v[26:27], v[0:1], v[0:1]
	v_pk_mov_b32 v[28:29], v[0:1], v[0:1]
	v_pk_mov_b32 v[30:31], v[0:1], v[0:1]
	v_pk_mov_b32 v[32:33], v[0:1], v[0:1]
	v_pk_mov_b32 v[34:35], v[0:1], v[0:1]
	v_pk_mov_b32 v[36:37], v[0:1], v[0:1]
	v_pk_mov_b32 v[38:39], v[0:1], v[0:1]
	v_pk_mov_b32 v[40:41], v[0:1], v[0:1]
	v_pk_mov_b32 v[42:43], v[0:1], v[0:1]
	v_pk_mov_b32 v[44:45], v[0:1], v[0:1]
	v_pk_mov_b32 v[46:47], v[0:1], v[0:1]
	v_pk_mov_b32 v[48:49], v[0:1], v[0:1]
	v_pk_mov_b32 v[50:51], v[0:1], v[0:1]
	v_pk_mov_b32 v[52:53], v[0:1], v[0:1]
	v_pk_mov_b32 v[54:55], v[0:1], v[0:1]
	v_pk_mov_b32 v[56:57], v[0:1], v[0:1]
	v_pk_mov_b32 v[58:59], v[0:1], v[0:1]
	v_pk_mov_b32 v[60:61], v[0:1], v[0:1]
	v_pk_mov_b32 v[62:63], v[0:1], v[0:1]
	v_pk_mov_b32 v[64:65], v[0:1], v[0:1]
	v_pk_mov_b32 v[66:67], v[0:1], v[0:1]
	v_pk_mov_b32 v[68:69], v[0:1], v[0:1]
	v_pk_mov_b32 v[70:71], v[0:1], v[0:1]
	v_pk_mov_b32 v[72:73], v[0:1], v[0:1]
	v_pk_mov_b32 v[74:75], v[0:1], v[0:1]
	v_pk_mov_b32 v[76:77], v[0:1], v[0:1]
	v_pk_mov_b32 v[78:79], v[0:1], v[0:1]
	v_pk_mov_b32 v[80:81], v[0:1], v[0:1]
	v_pk_mov_b32 v[82:83], v[0:1], v[0:1]
	v_pk_mov_b32 v[84:85], v[0:1], v[0:1]
	v_pk_mov_b32 v[86:87], v[0:1], v[0:1]
	v_pk_mov_b32 v[88:89], v[0:1], v[0:1]
	v_pk_mov_b32 v[90:91], v[0:1], v[0:1]
	v_pk_mov_b32 v[92:93], v[0:1], v[0:1]
	v_pk_mov_b32 v[94:95], v[0:1], v[0:1]
	v_pk_mov_b32 v[96:97], v[0:1], v[0:1]
	v_pk_mov_b32 v[98:99], v[0:1], v[0:1]
	v_pk_mov_b32 v[100:101], v[0:1], v[0:1]
	v_pk_mov_b32 v[102:103], v[0:1], v[0:1]
	v_pk_mov_b32 v[104:105], v[0:1], v[0:1]
	v_pk_mov_b32 v[106:107], v[0:1], v[0:1]
	v_pk_mov_b32 v[108:109], v[0:1], v[0:1]
	v_pk_mov_b32 v[110:111], v[0:1], v[0:1]
	v_pk_mov_b32 v[112:113], v[0:1], v[0:1]
	v_pk_mov_b32 v[114:115], v[0:1], v[0:1]
	v_pk_mov_b32 v[116:117], v[0:1], v[0:1]
	v_pk_mov_b32 v[118:119], v[0:1], v[0:1]
	v_pk_mov_b32 v[120:121], v[0:1], v[0:1]
	v_pk_mov_b32 v[122:123], v[0:1], v[0:1]
	v_pk_mov_b32 v[124:125], v[0:1], v[0:1]
	v_pk_mov_b32 v[126:127], v[0:1], v[0:1]
	s_branch .LBB0_1033

; #define PG8_BAR __builtin_amdgcn_s_barrier()
; template <class Epi>
; __device__ __forceinline__ void gemm_phase(LAS unsigned char* lds, const int tid, const Gemm g, const StaticOrder& S, const Epi& E) {
;     ...
;                 const char* sp = (const char*)E.ss + (size_t)cur.pm * (256 * 64) + (size_t)tid * 16;
;     ...
; #pragma unroll
;         for (int a = 0; a < 2; ++a)
; #pragma unroll
;             for (int b = 0; b < 2; ++b)
; #pragma unroll
;                 for (int m = 0; m < 4; ++m)
; #pragma unroll
;                     for (int n = 0; n < 2; ++n) acc[a][b][m][n] = (f32x4){0.f, 0.f, 0.f, 0.f};
;         cur = nxt; cA = nA; cB = nB; ++ui;
;         if (wr == 1) PG8_BAR;
.Lzskip_8:
	s_and_b64 s[34:35], s[2:3], exec
	s_cselect_b32 s19, s23, s31
	s_cselect_b32 s21, s22, s30
	s_cselect_b32 s33, s25, s29
	s_cselect_b32 s56, s24, s28
	s_ashr_i32 s5, s4, 31
	s_lshl_b64 s[34:35], s[4:5], 14
	s_add_u32 s5, s28, 0x100
	s_addc_u32 s57, s29, 0
	v_lshl_add_u64 v[148:149], v[138:139], 0, s[34:35]
	s_add_u32 s28, s30, 0x40080
	v_mov_b32_e32 v0, 0
	v_mov_b32_e32 v1, 0
	v_lshl_add_u64 v[150:151], v[148:149], 0, s[16:17]
	s_addc_u32 s29, s31, 0
	s_mov_b32 s58, 0
	v_pk_mov_b32 v[2:3], v[0:1], v[0:1]
	v_pk_mov_b32 v[4:5], v[0:1], v[0:1]
	v_pk_mov_b32 v[6:7], v[0:1], v[0:1]
	v_pk_mov_b32 v[8:9], v[0:1], v[0:1]
	v_pk_mov_b32 v[10:11], v[0:1], v[0:1]
	v_pk_mov_b32 v[12:13], v[0:1], v[0:1]
	v_pk_mov_b32 v[14:15], v[0:1], v[0:1]
	v_pk_mov_b32 v[16:17], v[0:1], v[0:1]
	v_pk_mov_b32 v[18:19], v[0:1], v[0:1]
	v_pk_mov_b32 v[20:21], v[0:1], v[0:1]
	v_pk_mov_b32 v[22:23], v[0:1], v[0:1]
	v_pk_mov_b32 v[24:25], v[0:1], v[0:1]
	v_pk_mov_b32 v[26:27], v[0:1], v[0:1]
	v_pk_mov_b32 v[28:29], v[0:1], v[0:1]
	v_pk_mov_b32 v[30:31], v[0:1], v[0:1]
	v_pk_mov_b32 v[32:33], v[0:1], v[0:1]
	v_pk_mov_b32 v[34:35], v[0:1], v[0:1]
	v_pk_mov_b32 v[36:37], v[0:1], v[0:1]
	v_pk_mov_b32 v[38:39], v[0:1], v[0:1]
	v_pk_mov_b32 v[40:41], v[0:1], v[0:1]
	v_pk_mov_b32 v[42:43], v[0:1], v[0:1]
	v_pk_mov_b32 v[44:45], v[0:1], v[0:1]
	v_pk_mov_b32 v[46:47], v[0:1], v[0:1]
	v_pk_mov_b32 v[48:49], v[0:1], v[0:1]
	v_pk_mov_b32 v[50:51], v[0:1], v[0:1]
	v_pk_mov_b32 v[52:53], v[0:1], v[0:1]
	v_pk_mov_b32 v[54:55], v[0:1], v[0:1]
	v_pk_mov_b32 v[56:57], v[0:1], v[0:1]
	v_pk_mov_b32 v[58:59], v[0:1], v[0:1]
	v_pk_mov_b32 v[60:61], v[0:1], v[0:1]
	v_pk_mov_b32 v[62:63], v[0:1], v[0:1]
	v_pk_mov_b32 v[64:65], v[0:1], v[0:1]
	v_pk_mov_b32 v[66:67], v[0:1], v[0:1]
	v_pk_mov_b32 v[68:69], v[0:1], v[0:1]
	v_pk_mov_b32 v[70:71], v[0:1], v[0:1]
	v_pk_mov_b32 v[72:73], v[0:1], v[0:1]
	v_pk_mov_b32 v[74:75], v[0:1], v[0:1]
	v_pk_mov_b32 v[76:77], v[0:1], v[0:1]
	v_pk_mov_b32 v[78:79], v[0:1], v[0:1]
	v_pk_mov_b32 v[80:81], v[0:1], v[0:1]
	v_pk_mov_b32 v[82:83], v[0:1], v[0:1]
	v_pk_mov_b32 v[84:85], v[0:1], v[0:1]
	v_pk_mov_b32 v[86:87], v[0:1], v[0:1]
	v_pk_mov_b32 v[88:89], v[0:1], v[0:1]
	v_pk_mov_b32 v[90:91], v[0:1], v[0:1]
	v_pk_mov_b32 v[92:93], v[0:1], v[0:1]
	v_pk_mov_b32 v[94:95], v[0:1], v[0:1]
	v_pk_mov_b32 v[96:97], v[0:1], v[0:1]
	v_pk_mov_b32 v[98:99], v[0:1], v[0:1]
	v_pk_mov_b32 v[100:101], v[0:1], v[0:1]
	v_pk_mov_b32 v[102:103], v[0:1], v[0:1]
	v_pk_mov_b32 v[104:105], v[0:1], v[0:1]
	v_pk_mov_b32 v[106:107], v[0:1], v[0:1]
	v_pk_mov_b32 v[108:109], v[0:1], v[0:1]
	v_pk_mov_b32 v[110:111], v[0:1], v[0:1]
	v_pk_mov_b32 v[112:113], v[0:1], v[0:1]
	v_pk_mov_b32 v[114:115], v[0:1], v[0:1]
	v_pk_mov_b32 v[116:117], v[0:1], v[0:1]
	v_pk_mov_b32 v[118:119], v[0:1], v[0:1]
	v_pk_mov_b32 v[120:121], v[0:1], v[0:1]
	v_pk_mov_b32 v[122:123], v[0:1], v[0:1]
	v_pk_mov_b32 v[124:125], v[0:1], v[0:1]
	v_pk_mov_b32 v[126:127], v[0:1], v[0:1]
	s_branch .LBB0_1313

; #define PG8_BAR __builtin_amdgcn_s_barrier()
; template <class Epi>
; __device__ __forceinline__ void gemm_phase(LAS unsigned char* lds, const int tid, const Gemm g, const StaticOrder& S, const Epi& E) {
;     ...
;                 const char* sp = (const char*)E.ss + (size_t)cur.pm * (256 * 64) + (size_t)tid * 16;
;     ...
; #pragma unroll
;         for (int a = 0; a < 2; ++a)
; #pragma unroll
;             for (int b = 0; b < 2; ++b)
; #pragma unroll
;                 for (int m = 0; m < 4; ++m)
; #pragma unroll
;                     for (int n = 0; n < 2; ++n) acc[a][b][m][n] = (f32x4){0.f, 0.f, 0.f, 0.f};
;         cur = nxt; cA = nA; cB = nB; ++ui;
;         if (wr == 1) PG8_BAR;
.Lzskip_13:
	s_and_b64 s[34:35], s[0:1], exec
	s_cselect_b32 s19, s23, s31
	s_cselect_b32 s21, s22, s30
	s_cselect_b32 s52, s25, s29
	s_cselect_b32 s53, s24, s28
	s_ashr_i32 s27, s26, 31
	s_lshl_b64 s[34:35], s[26:27], 14
	s_add_u32 s27, s28, 0x100
	s_addc_u32 s54, s29, 0
	v_lshl_add_u64 v[128:129], v[192:193], 0, s[34:35]
	s_add_u32 s28, s30, 0x40080
	v_mov_b32_e32 v0, 0
	v_mov_b32_e32 v1, 0
	v_lshl_add_u64 v[130:131], v[128:129], 0, s[6:7]
	s_addc_u32 s29, s31, 0
	s_mov_b32 s55, 0
	v_pk_mov_b32 v[2:3], v[0:1], v[0:1]
	v_pk_mov_b32 v[4:5], v[0:1], v[0:1]
	v_pk_mov_b32 v[6:7], v[0:1], v[0:1]
	v_pk_mov_b32 v[8:9], v[0:1], v[0:1]
	v_pk_mov_b32 v[10:11], v[0:1], v[0:1]
	v_pk_mov_b32 v[12:13], v[0:1], v[0:1]
	v_pk_mov_b32 v[14:15], v[0:1], v[0:1]
	v_pk_mov_b32 v[16:17], v[0:1], v[0:1]
	v_pk_mov_b32 v[18:19], v[0:1], v[0:1]
	v_pk_mov_b32 v[20:21], v[0:1], v[0:1]
	v_pk_mov_b32 v[22:23], v[0:1], v[0:1]
	v_pk_mov_b32 v[24:25], v[0:1], v[0:1]
	v_pk_mov_b32 v[26:27], v[0:1], v[0:1]
	v_pk_mov_b32 v[28:29], v[0:1], v[0:1]
	v_pk_mov_b32 v[30:31], v[0:1], v[0:1]
	v_pk_mov_b32 v[32:33], v[0:1], v[0:1]
	v_pk_mov_b32 v[34:35], v[0:1], v[0:1]
	v_pk_mov_b32 v[36:37], v[0:1], v[0:1]
	v_pk_mov_b32 v[38:39], v[0:1], v[0:1]
	v_pk_mov_b32 v[40:41], v[0:1], v[0:1]
	v_pk_mov_b32 v[42:43], v[0:1], v[0:1]
	v_pk_mov_b32 v[44:45], v[0:1], v[0:1]
	v_pk_mov_b32 v[46:47], v[0:1], v[0:1]
	v_pk_mov_b32 v[48:49], v[0:1], v[0:1]
	v_pk_mov_b32 v[50:51], v[0:1], v[0:1]
	v_pk_mov_b32 v[52:53], v[0:1], v[0:1]
	v_pk_mov_b32 v[54:55], v[0:1], v[0:1]
	v_pk_mov_b32 v[56:57], v[0:1], v[0:1]
	v_pk_mov_b32 v[58:59], v[0:1], v[0:1]
	v_pk_mov_b32 v[60:61], v[0:1], v[0:1]
	v_pk_mov_b32 v[62:63], v[0:1], v[0:1]
	v_pk_mov_b32 v[64:65], v[0:1], v[0:1]
	v_pk_mov_b32 v[66:67], v[0:1], v[0:1]
	v_pk_mov_b32 v[68:69], v[0:1], v[0:1]
	v_pk_mov_b32 v[70:71], v[0:1], v[0:1]
	v_pk_mov_b32 v[72:73], v[0:1], v[0:1]
	v_pk_mov_b32 v[74:75], v[0:1], v[0:1]
	v_pk_mov_b32 v[76:77], v[0:1], v[0:1]
	v_pk_mov_b32 v[78:79], v[0:1], v[0:1]
	v_pk_mov_b32 v[80:81], v[0:1], v[0:1]
	v_pk_mov_b32 v[82:83], v[0:1], v[0:1]
	v_pk_mov_b32 v[84:85], v[0:1], v[0:1]
	v_pk_mov_b32 v[86:87], v[0:1], v[0:1]
	v_pk_mov_b32 v[88:89], v[0:1], v[0:1]
	v_pk_mov_b32 v[90:91], v[0:1], v[0:1]
	v_pk_mov_b32 v[92:93], v[0:1], v[0:1]
	v_pk_mov_b32 v[94:95], v[0:1], v[0:1]
	v_pk_mov_b32 v[96:97], v[0:1], v[0:1]
	v_pk_mov_b32 v[98:99], v[0:1], v[0:1]
	v_pk_mov_b32 v[100:101], v[0:1], v[0:1]
	v_pk_mov_b32 v[102:103], v[0:1], v[0:1]
	v_pk_mov_b32 v[104:105], v[0:1], v[0:1]
	v_pk_mov_b32 v[106:107], v[0:1], v[0:1]
	v_pk_mov_b32 v[108:109], v[0:1], v[0:1]
	v_pk_mov_b32 v[110:111], v[0:1], v[0:1]
	v_pk_mov_b32 v[112:113], v[0:1], v[0:1]
	v_pk_mov_b32 v[114:115], v[0:1], v[0:1]
	v_pk_mov_b32 v[116:117], v[0:1], v[0:1]
	v_pk_mov_b32 v[118:119], v[0:1], v[0:1]
	v_pk_mov_b32 v[120:121], v[0:1], v[0:1]
	v_pk_mov_b32 v[122:123], v[0:1], v[0:1]
	v_pk_mov_b32 v[124:125], v[0:1], v[0:1]
	v_pk_mov_b32 v[126:127], v[0:1], v[0:1]
	s_branch .LBB0_2037
